# attention queue order: heavy half (qb 15..8) then light half, 8 query blocks of a batch adjacent
# speedup vs baseline: 1.0038x; 1.0038x over previous
; __device__ __forceinline__ void unpack8(u32x4v w, float* f) { f[0] = bflo(w.x); f[1] = bfhi(w.x); f[2] = bflo(w.y); f[3] = bfhi(w.y); f[4] = bflo(w.z); f[5] = bfhi(w.z); f[6] = bflo(w.w); f[7] = bfhi(w.w); }
; __device__ __forceinline__ void attn_unit(const Args& c, int l, int b, int h, int qb, float lam, float lam_init, LAS unsigned char* lds) {
;     ...
;         const bf16* qrow = P + (seq0 + 128 * qb + 16 * w + r) * PW + QC;
; #pragma unroll
;         for (int m = 0; m < 2; ++m) {
;             float f[16];
;             unpack8(*(const u32x4v*)(qrow + m * 64 + q4 * 8), f); unpack8(*(const u32x4v*)(qrow + m * 64 + 32 + q4 * 8), f + 8);
;             float ss = 0.f;
; #pragma unroll
;             for (int e = 0; e < 16; ++e) ss += f[e] * f[e];
;             ss += __shfl_xor(ss, 16); ss += __shfl_xor(ss, 32);
; __device__ __forceinline__ void m2_phase(const Args& c, int l, LAS unsigned char* lds, int G, int mode, bool dry, int cidx) {
;     ...
;             const int q = *slot;
;             if (q >= 128) break;
;             const int qb = 15 - (q >> 3);
.LBB0_243:
	s_or_b64 exec, exec, s[2:3]
	v_mov_b32_e32 v0, s39
	s_waitcnt lgkmcnt(0)
	s_barrier
	ds_read_b32 v0, v0
	s_movk_i32 s2, 0x7f
	s_waitcnt lgkmcnt(0)
	v_cmp_lt_i32_e32 vcc, s2, v0
	v_readfirstlane_b32 s4, v0
	s_mov_b64 s[2:3], -1
	s_cbranch_vccnz .LBB0_240
	v_readlane_b32 s8, v252, 57
	s_and_b32 s6, s4, 7
	s_lshr_b32 s7, s4, 6
	s_lshl_b32 s7, s7, 3
	s_add_i32 s6, s6, s7
	v_readlane_b32 s10, v252, 59
	v_readlane_b32 s11, v252, 60
	s_sub_i32 s22, 15, s6
	v_mov_b32_e32 v106, v179
	s_mov_b64 s[38:39], s[10:11]
	v_readlane_b32 s9, v252, 58
	s_mov_b32 s8, 0
	s_add_u32 s2, s38, 0xa800000
	s_addc_u32 s3, s39, 0
	s_lshl_b32 s4, s4, 8
	s_ashr_i32 s9, s8, 31
	s_and_b32 s18, s4, 0x3800
	s_lshl_b64 s[4:5], s[8:9], 3
	v_readlane_b32 s8, v251, 0
	v_readlane_b32 s9, v251, 1
	s_add_u32 s24, s8, s4
	s_addc_u32 s25, s9, s5
	s_load_dwordx4 s[8:11], s[24:25], 0xb0
	v_readfirstlane_b32 s4, v106
	v_and_b32_e32 v107, 15, v106
	v_mov_b64_e32 v[18:19], s[2:3]
	v_bfe_u32 v108, v106, 4, 2
	s_waitcnt lgkmcnt(0)
	s_add_u32 s12, s8, s30
	s_addc_u32 s13, s9, s31
	s_ashr_i32 s4, s4, 2
	s_lshl_b32 s7, s22, 7
	s_and_b32 s8, s4, -16
	s_add_i32 s5, s7, s18
	s_ashr_i32 s4, s8, 31
	s_add_u32 s5, s8, s5
	v_or_b32_e32 v184, s5, v107
	s_addc_u32 s9, s4, 0
	v_mad_u64_u32 v[2:3], s[4:5], v184, s27, v[18:19]
	v_mad_i32_i24 v3, s9, v196, v3
	s_lshl_b32 s4, s19, 1
	s_mov_b32 s5, s15
	v_lshl_add_u64 v[2:3], v[2:3], 0, s[4:5]
	v_lshlrev_b32_e32 v0, 4, v108
	v_lshl_add_u64 v[2:3], v[2:3], 0, v[0:1]
	s_movk_i32 s5, 0x1000
	v_add_co_u32_e32 v2, vcc, s5, v2
	v_lshlrev_b32_e32 v14, 5, v108
	s_nop 0
	v_addc_co_u32_e32 v3, vcc, 0, v3, vcc
	flat_load_dwordx4 v[26:29], v[2:3] offset:3904
	flat_load_dwordx4 v[30:33], v[2:3] offset:4032
	flat_load_dwordx4 v[34:37], v[2:3] offset:3840
	flat_load_dwordx4 v[38:41], v[2:3] offset:3968
	s_nop 0
	global_load_dwordx4 v[2:5], v14, s[12:13] offset:144
	global_load_dwordx4 v[6:9], v14, s[12:13] offset:128
	global_load_dwordx4 v[10:13], v14, s[12:13] offset:16
	s_nop 0
	global_load_dwordx4 v[14:17], v14, s[12:13]
	v_ashrrev_i32_e32 v186, 3, v106
	s_lshl_b32 s20, s0, 1
	s_mov_b32 s21, s15
	s_lshl_b32 s28, s1, 1
	s_mov_b32 s29, s15
	s_add_u32 s10, s10, s30
	s_addc_u32 s11, s11, s31
	v_lshlrev_b32_e32 v208, 2, v108
	s_add_i32 s8, s8, s7
	s_movk_i32 s7, 0x110
	v_or_b32_e32 v209, s8, v107
	v_mov_b32_e32 v108, v1
	v_mov_b32_e32 v109, v1
	s_mov_b32 s5, 0
	v_mov_b32_e32 v185, s9
	v_ashrrev_i32_e32 v187, 31, v186
	s_sub_i32 s34, 16, s6
	v_mov_b32_e32 v216, 0
	v_mov_b32_e32 v192, 0xff800000
	v_mov_b32_e32 v148, 0xff800000
	v_mov_b32_e32 v215, 0
	s_mov_b32 s35, 0
	s_waitcnt vmcnt(0) lgkmcnt(0)
	v_lshlrev_b32_e32 v42, 16, v29
	v_and_b32_e32 v43, 0xffff0000, v29
	v_lshlrev_b32_e32 v20, 16, v33
	v_and_b32_e32 v21, 0xffff0000, v33
	v_lshlrev_b32_e32 v44, 16, v28
	v_and_b32_e32 v45, 0xffff0000, v28
	v_lshlrev_b32_e32 v22, 16, v32
	v_and_b32_e32 v23, 0xffff0000, v32
	v_lshlrev_b32_e32 v28, 16, v27
	v_and_b32_e32 v29, 0xffff0000, v27
	v_lshlrev_b32_e32 v24, 16, v31
	v_and_b32_e32 v25, 0xffff0000, v31
	v_lshlrev_b32_e32 v32, 16, v26
	v_and_b32_e32 v33, 0xffff0000, v26
	v_lshlrev_b32_e32 v26, 16, v30
	v_and_b32_e32 v27, 0xffff0000, v30
	v_lshlrev_b32_e32 v30, 16, v37
	v_and_b32_e32 v31, 0xffff0000, v37
	v_lshlrev_b32_e32 v46, 16, v41
	v_and_b32_e32 v47, 0xffff0000, v41
	v_lshlrev_b32_e32 v48, 16, v36
	v_and_b32_e32 v49, 0xffff0000, v36
	v_lshlrev_b32_e32 v36, 16, v40
	v_and_b32_e32 v37, 0xffff0000, v40
	v_lshlrev_b32_e32 v40, 16, v35
	v_and_b32_e32 v41, 0xffff0000, v35
	v_and_b32_e32 v51, 0xffff0000, v34
	v_and_b32_e32 v35, 0xffff0000, v38
	v_lshlrev_b32_e32 v50, 16, v34
	v_lshlrev_b32_e32 v34, 16, v38
	v_mov_b32_e32 v82, v35
	v_mov_b32_e32 v83, v51
	v_lshlrev_b32_e32 v58, 16, v39
	v_mov_b32_e32 v80, v34
	v_mov_b32_e32 v81, v50
	v_pk_mul_f32 v[82:83], v[82:83], v[82:83]
	v_and_b32_e32 v59, 0xffff0000, v39
	v_mov_b32_e32 v76, v58
	v_mov_b32_e32 v77, v40
	v_pk_fma_f32 v[80:81], v[80:81], v[80:81], v[82:83]
	v_mov_b32_e32 v78, v59
	v_mov_b32_e32 v79, v41
	v_pk_fma_f32 v[76:77], v[76:77], v[76:77], v[80:81]
	v_mov_b32_e32 v72, v36
	v_mov_b32_e32 v73, v48
	v_pk_fma_f32 v[76:77], v[78:79], v[78:79], v[76:77]
	v_mov_b32_e32 v74, v37
	v_mov_b32_e32 v75, v49
	v_pk_fma_f32 v[72:73], v[72:73], v[72:73], v[76:77]
	v_mov_b32_e32 v68, v46
	v_mov_b32_e32 v69, v30
	v_pk_fma_f32 v[72:73], v[74:75], v[74:75], v[72:73]
	v_pk_mul_f32 v[64:65], v[32:33], v[32:33]
	v_pk_mul_f32 v[66:67], v[26:27], v[26:27]
	v_mov_b32_e32 v70, v47
	v_mov_b32_e32 v71, v31
	v_pk_fma_f32 v[68:69], v[68:69], v[68:69], v[72:73]
	v_pk_mul_f32 v[60:61], v[28:29], v[28:29]
	v_pk_fma_f32 v[68:69], v[70:71], v[70:71], v[68:69]
	v_mov_b32_e32 v70, v66
	v_mov_b32_e32 v71, v64
	v_pk_mul_f32 v[62:63], v[24:25], v[24:25]
	v_pk_add_f32 v[68:69], v[70:71], v[68:69]
	v_mov_b32_e32 v64, v67
	v_pk_add_f32 v[64:65], v[64:65], v[68:69]
	v_mov_b32_e32 v66, v62
	v_mov_b32_e32 v67, v60
	v_pk_mul_f32 v[54:55], v[44:45], v[44:45]
	v_pk_mul_f32 v[56:57], v[22:23], v[22:23]
	v_pk_add_f32 v[64:65], v[66:67], v[64:65]
	v_mov_b32_e32 v60, v63
	v_pk_add_f32 v[60:61], v[60:61], v[64:65]
	v_mov_b32_e32 v62, v56
	v_mov_b32_e32 v63, v54
	v_pk_mul_f32 v[38:39], v[42:43], v[42:43]
	v_pk_mul_f32 v[52:53], v[20:21], v[20:21]
	v_pk_add_f32 v[60:61], v[62:63], v[60:61]
	v_mov_b32_e32 v54, v57
	v_pk_add_f32 v[54:55], v[54:55], v[60:61]
	v_mov_b32_e32 v56, v52
	v_mov_b32_e32 v57, v38
	v_pk_add_f32 v[54:55], v[56:57], v[54:55]
	v_mov_b32_e32 v38, v53
	v_pk_add_f32 v[38:39], v[38:39], v[54:55]
	ds_bpermute_b32 v53, v205, v39
	ds_bpermute_b32 v52, v205, v38
	s_waitcnt lgkmcnt(0)
; __device__ __forceinline__ unsigned pk2(float lo, float hi) { f32x2_t v = {lo, hi}; bf16x2_t b = __builtin_convertvector(v, bf16x2_t); return __builtin_bit_cast(unsigned, b); }
; #define ATT_FETCH(KT) do { _Pragma("unroll") for (int hh = 0; hh < 2; ++hh) { const bf16* krow = P + (seq0 + 128 * (KT) + 64 * hh + skey) * PW; \
;         gk0[hh] = *(const u32x4v*)(krow + KC + part * 16); gk1[hh] = *(const u32x4v*)(krow + KC + part * 16 + 8); \
;         gv0[hh] = *(const u32x4v*)(krow + VC + part * 16); gv1[hh] = *(const u32x4v*)(krow + VC + part * 16 + 8); } } while (0)
; __device__ __forceinline__ void attn_unit(const Args& c, int l, int b, int h, int qb, float lam, float lam_init, LAS unsigned char* lds) {
;     ...
; #pragma unroll
;             for (int e = 0; e < 16; ++e) ss += f[e] * f[e];
;             ss += __shfl_xor(ss, 16); ss += __shfl_xor(ss, 32);
;             const float sc = rsqrtf(ss * (1.f / 64.f) + 1e-6f) * (0.125f * 1.4426950408889634f);
; #pragma unroll
;             for (int ks = 0; ks < 2; ++ks) { u32x4v o; const float* g = f + 8 * ks; const float* wn = qnw + ks * 32 + q4 * 8;
;                 o.x = pk2(g[0] * sc * wn[0], g[1] * sc * wn[1]); o.y = pk2(g[2] * sc * wn[2], g[3] * sc * wn[3]); o.z = pk2(g[4] * sc * wn[4], g[5] * sc * wn[5]); o.w = pk2(g[6] * sc * wn[6], g[7] * sc * wn[7]);
;                 qf[m][ks] = __builtin_bit_cast(bf16x8, o); }
;         }
;     }
;     f32x4 O[2][8];
; #pragma unroll
;     for (int m = 0; m < 2; ++m)
; #pragma unroll
;         for (int vb = 0; vb < 8; ++vb) O[m][vb] = (f32x4){0.f, 0.f, 0.f, 0.f};
;     float mrow[2] = {-INFINITY, -INFINITY}, lrow[2] = {0.f, 0.f};
;     const int NT = qb + 1;
;     const int skey = tid >> 3, part = tid & 7;
;     const float* kwp = knw + (part & 3) * 16;
;     u32x4v gk0[2], gk1[2], gv0[2], gv1[2];
;     ...
;     ATT_FETCH(0);
	v_pk_add_f32 v[38:39], v[38:39], v[52:53]
	ds_bpermute_b32 v53, v206, v39
	ds_bpermute_b32 v52, v206, v38
	s_waitcnt lgkmcnt(0)
	v_pk_add_f32 v[38:39], v[38:39], v[52:53]
	s_nop 0
	v_pk_fma_f32 v[38:39], v[38:39], s[26:27], v[178:179] op_sel_hi:[1,0,0]
	s_nop 0
	v_mul_f32_e32 v52, 0x4b800000, v39
	v_cmp_gt_f32_e32 vcc, s33, v39
	s_nop 1
	v_cndmask_b32_e32 v39, v39, v52, vcc
	v_rsq_f32_e32 v39, v39
	s_nop 0
	v_mul_f32_e32 v52, 0x45800000, v39
	v_cndmask_b32_e32 v39, v39, v52, vcc
	v_mul_f32_e32 v52, 0x3e38aa3b, v39
	v_pk_mul_f32 v[28:29], v[52:53], v[28:29] op_sel_hi:[0,1]
	v_pk_mul_f32 v[32:33], v[52:53], v[32:33] op_sel_hi:[0,1]
	v_pk_mul_f32 v[28:29], v[8:9], v[28:29]
	v_pk_mul_f32 v[60:61], v[52:53], v[50:51] op_sel_hi:[0,1]
	v_pk_mul_f32 v[30:31], v[52:53], v[30:31] op_sel_hi:[0,1]
	v_pk_mul_f32 v[42:43], v[52:53], v[42:43] op_sel_hi:[0,1]
	v_cvt_pk_bf16_f32 v51, v28, v29
	v_pk_mul_f32 v[28:29], v[6:7], v[32:33]
	v_pk_mul_f32 v[48:49], v[52:53], v[48:49] op_sel_hi:[0,1]
	v_pk_mul_f32 v[44:45], v[52:53], v[44:45] op_sel_hi:[0,1]
	v_pk_mul_f32 v[42:43], v[4:5], v[42:43]
	v_cvt_pk_bf16_f32 v50, v28, v29
	v_pk_mul_f32 v[28:29], v[12:13], v[30:31]
	v_lshlrev_b32_e32 v30, 4, v106
	v_add_u32_e32 v39, s18, v186
	v_pk_mul_f32 v[40:41], v[52:53], v[40:41] op_sel_hi:[0,1]
	v_cvt_pk_bf16_f32 v53, v42, v43
	v_pk_mul_f32 v[42:43], v[2:3], v[44:45]
	v_cvt_pk_bf16_f32 v57, v28, v29
	v_pk_mul_f32 v[28:29], v[10:11], v[48:49]
	v_and_b32_e32 v30, 0x70, v30
	v_mad_i64_i32 v[32:33], s[12:13], v39, s27, v[18:19]
	v_cvt_pk_bf16_f32 v52, v42, v43
	v_cvt_pk_bf16_f32 v56, v28, v29
	v_pk_mul_f32 v[28:29], v[16:17], v[40:41]
	v_lshl_add_u64 v[40:41], v[32:33], 0, s[20:21]
	v_lshlrev_b32_e32 v42, 1, v30
	v_mov_b32_e32 v43, v1
	v_lshl_add_u64 v[32:33], v[32:33], 0, s[28:29]
	v_lshl_add_u64 v[40:41], v[40:41], 0, v[42:43]
	v_lshl_add_u64 v[32:33], v[32:33], 0, v[42:43]
	flat_load_dwordx4 v[66:69], v[40:41]
	flat_load_dwordx4 v[70:73], v[40:41] offset:16
	flat_load_dwordx4 v[78:81], v[32:33]
	flat_load_dwordx4 v[82:85], v[32:33] offset:16
	v_add_u32_e32 v32, 64, v39
	v_mad_i64_i32 v[18:19], s[12:13], v32, s27, v[18:19]
	v_lshl_add_u64 v[32:33], v[18:19], 0, s[20:21]
	v_lshl_add_u64 v[18:19], v[18:19], 0, s[28:29]
	v_lshl_add_u64 v[32:33], v[32:33], 0, v[42:43]
	v_lshl_add_u64 v[18:19], v[18:19], 0, v[42:43]
	flat_load_dwordx4 v[90:93], v[32:33]
	flat_load_dwordx4 v[94:97], v[32:33] offset:16
	flat_load_dwordx4 v[98:101], v[18:19]
	flat_load_dwordx4 v[102:105], v[18:19] offset:16
	v_mul_f32_e32 v31, 0x4b800000, v38
	v_cmp_gt_f32_e32 vcc, s33, v38
	v_cvt_pk_bf16_f32 v55, v28, v29
	s_nop 0
	v_cndmask_b32_e32 v18, v38, v31, vcc
	v_rsq_f32_e32 v31, v18
	v_pk_mul_f32 v[18:19], v[14:15], v[60:61]
	s_nop 0
	v_cvt_pk_bf16_f32 v54, v18, v19
	v_mul_f32_e32 v18, 0x45800000, v31
	v_cndmask_b32_e32 v18, v31, v18, vcc
	v_mul_f32_e32 v18, 0x3e38aa3b, v18
	v_pk_mul_f32 v[28:29], v[18:19], v[34:35] op_sel_hi:[0,1]
	v_pk_mul_f32 v[14:15], v[14:15], v[28:29]
	s_nop 0
	v_cvt_pk_bf16_f32 v74, v14, v15
	v_pk_mul_f32 v[14:15], v[18:19], v[58:59] op_sel_hi:[0,1]
	v_pk_mul_f32 v[14:15], v[16:17], v[14:15]
	s_nop 0
	v_cvt_pk_bf16_f32 v75, v14, v15
	v_pk_mul_f32 v[14:15], v[18:19], v[36:37] op_sel_hi:[0,1]
	v_pk_mul_f32 v[10:11], v[10:11], v[14:15]
	s_nop 0
	v_cvt_pk_bf16_f32 v76, v10, v11
	v_pk_mul_f32 v[10:11], v[18:19], v[46:47] op_sel_hi:[0,1]
	v_pk_mul_f32 v[10:11], v[12:13], v[10:11]
	s_nop 0
	v_cvt_pk_bf16_f32 v77, v10, v11
	v_pk_mul_f32 v[10:11], v[18:19], v[26:27] op_sel_hi:[0,1]
	v_pk_mul_f32 v[6:7], v[6:7], v[10:11]
	s_nop 0
	v_cvt_pk_bf16_f32 v86, v6, v7
	v_pk_mul_f32 v[6:7], v[18:19], v[24:25] op_sel_hi:[0,1]
	v_pk_mul_f32 v[6:7], v[8:9], v[6:7]
	s_nop 0
	v_cvt_pk_bf16_f32 v87, v6, v7
	v_pk_mul_f32 v[6:7], v[18:19], v[22:23] op_sel_hi:[0,1]
	v_pk_mul_f32 v[2:3], v[2:3], v[6:7]
	s_nop 0
	v_cvt_pk_bf16_f32 v88, v2, v3
	v_pk_mul_f32 v[2:3], v[18:19], v[20:21] op_sel_hi:[0,1]
	v_pk_mul_f32 v[2:3], v[4:5], v[2:3]
	s_nop 0
	v_cvt_pk_bf16_f32 v89, v2, v3
	v_lshlrev_b32_e32 v2, 6, v106
	v_and_b32_e32 v2, 0xc0, v2
	v_mov_b32_e32 v3, v1
	v_lshl_add_u64 v[188:189], s[10:11], 0, v[2:3]
	v_bfe_u32 v2, v106, 2, 2
	v_add_u32_e32 v3, 0, v0
	v_or_b32_e32 v0, v208, v2
	v_lshlrev_b32_e32 v2, 3, v106
	v_mul_u32_u24_e32 v0, 0x110, v0
	v_and_b32_e32 v2, 24, v2
	v_add3_u32 v210, 0, v0, v2
	v_mul_lo_u32 v0, v186, s7
	v_mul_u32_u24_e32 v2, 0x110, v107
	v_mov_b32_e32 v106, v1
	v_mov_b32_e32 v107, v1
	v_add3_u32 v211, 0, v42, v0
	v_lshlrev_b32_e32 v0, 1, v30
	v_add_u32_e32 v212, v3, v2
	v_mov_b64_e32 v[2:3], v[106:107]
	v_mov_b64_e32 v[10:11], v[106:107]
	v_mov_b64_e32 v[18:19], v[106:107]
	v_mov_b64_e32 v[58:59], v[106:107]
	v_mov_b64_e32 v[26:27], v[106:107]
	v_mov_b64_e32 v[34:35], v[106:107]
	v_mov_b64_e32 v[42:43], v[106:107]
	v_mov_b64_e32 v[112:113], v[108:109]
	v_mov_b64_e32 v[6:7], v[106:107]
	v_mov_b64_e32 v[14:15], v[106:107]
	v_mov_b64_e32 v[22:23], v[106:107]
	v_mov_b64_e32 v[62:63], v[106:107]
	v_mov_b64_e32 v[30:31], v[106:107]
	v_mov_b64_e32 v[38:39], v[106:107]
	v_mov_b64_e32 v[46:47], v[106:107]
	v_mov_b64_e32 v[4:5], v[108:109]
	v_mov_b64_e32 v[12:13], v[108:109]
	v_mov_b64_e32 v[20:21], v[108:109]
	v_mov_b64_e32 v[60:61], v[108:109]
	v_mov_b64_e32 v[28:29], v[108:109]
	v_mov_b64_e32 v[36:37], v[108:109]
	v_mov_b64_e32 v[44:45], v[108:109]
	v_mov_b64_e32 v[110:111], v[106:107]
	v_mov_b64_e32 v[8:9], v[108:109]
	v_mov_b64_e32 v[16:17], v[108:109]
	v_mov_b64_e32 v[24:25], v[108:109]
	v_mov_b64_e32 v[64:65], v[108:109]
	v_mov_b64_e32 v[32:33], v[108:109]
	v_mov_b64_e32 v[40:41], v[108:109]
	v_mov_b64_e32 v[48:49], v[108:109]
